# top-k popcount accumulation split 4 scalar + 4 vector per 8-row block
# speedup vs baseline: 1.0118x; 1.0118x over previous
; #define TK_GRP(g) { const int c0 = __popcll(__ballot(u[4 * (g)] >= cand)), c1 = __popcll(__ballot(u[4 * (g) + 1] >= cand)), c2 = __popcll(__ballot(u[4 * (g) + 2] >= cand)), c3 = __popcll(__ballot(u[4 * (g) + 3] >= cand)); cnt += (c0 + c1) + (c2 + c3); }
; __device__ __forceinline__ void indexer_unit(const Args& a, LAS unsigned char* lds, LAS unsigned long long* maskl, int b, int qblk, int wave, int lane) {
;     ...
;             unsigned T = 0u; bool exact = false; const int ng = (nr + 3) >> 2;
; #pragma unroll 1
;     ...
;                 const unsigned cand = T | (1u << bit); int cnt = 0;
;     ...
;                 switch (ng) {
;                     case 8: TK_GRP(7) [[fallthrough]];
;                     case 7: TK_GRP(6) [[fallthrough]];
;                     case 6: TK_GRP(5) [[fallthrough]];
;                     case 5: TK_GRP(4) [[fallthrough]];
;                     case 4: TK_GRP(3) [[fallthrough]];
;                     case 3: TK_GRP(2) [[fallthrough]];
;                     case 2: TK_GRP(1) [[fallthrough]];
;                     default: TK_GRP(0)
;                 }
;     ...
;                 if (cnt >= 256) { T = cand; if (cnt == 256) { exact = true; break; } }
;             }
.Ltk_bit:
	s_lshl_b32 s12, 1, s11
	s_or_b32 s13, s10, s12
	v_mov_b32_e32 v24, 0
	v_cmp_le_u32_e64 s[24:25], s13, v32
	v_cmp_le_u32_e64 s[26:27], s13, v33
	v_cmp_le_u32_e64 s[28:29], s13, v34
	v_cmp_le_u32_e64 s[30:31], s13, v35
	v_cmp_le_u32_e64 s[34:35], s13, v36
	v_cmp_le_u32_e64 s[36:37], s13, v37
	v_cmp_le_u32_e64 s[38:39], s13, v38
	v_cmp_le_u32_e64 s[40:41], s13, v39
	s_bcnt1_i32_b64 s42, s[24:25]
	s_bcnt1_i32_b64 s43, s[26:27]
	s_bcnt1_i32_b64 s44, s[28:29]
	s_bcnt1_i32_b64 s45, s[30:31]
	s_bcnt1_i32_b64 s46, s[34:35]
	s_bcnt1_i32_b64 s47, s[36:37]
	s_bcnt1_i32_b64 s48, s[38:39]
	s_bcnt1_i32_b64 s49, s[40:41]
	s_add_i32 s14, s42, s43
	s_add_i32 s14, s14, s44
	s_add_i32 s14, s14, s45
	v_add_u32_e32 v24, s46, v24
	v_add_u32_e32 v24, s47, v24
	v_add_u32_e32 v24, s48, v24
	v_add_u32_e32 v24, s49, v24
	s_cmp_lt_u32 s21, 2
	s_cbranch_scc1 .Ltk_dec
	v_cmp_le_u32_e64 s[24:25], s13, v40
	v_cmp_le_u32_e64 s[26:27], s13, v41
	v_cmp_le_u32_e64 s[28:29], s13, v42
	v_cmp_le_u32_e64 s[30:31], s13, v43
	v_cmp_le_u32_e64 s[34:35], s13, v44
	v_cmp_le_u32_e64 s[36:37], s13, v45
	v_cmp_le_u32_e64 s[38:39], s13, v46
	v_cmp_le_u32_e64 s[40:41], s13, v47
	s_bcnt1_i32_b64 s42, s[24:25]
	s_bcnt1_i32_b64 s43, s[26:27]
	s_bcnt1_i32_b64 s44, s[28:29]
	s_bcnt1_i32_b64 s45, s[30:31]
	s_bcnt1_i32_b64 s46, s[34:35]
	s_bcnt1_i32_b64 s47, s[36:37]
	s_bcnt1_i32_b64 s48, s[38:39]
	s_bcnt1_i32_b64 s49, s[40:41]
	s_add_i32 s14, s14, s42
	s_add_i32 s14, s14, s43
	s_add_i32 s14, s14, s44
	s_add_i32 s14, s14, s45
	v_add_u32_e32 v24, s46, v24
	v_add_u32_e32 v24, s47, v24
	v_add_u32_e32 v24, s48, v24
	v_add_u32_e32 v24, s49, v24
	s_cmp_lt_u32 s21, 3
	s_cbranch_scc1 .Ltk_dec
	v_cmp_le_u32_e64 s[24:25], s13, v48
	v_cmp_le_u32_e64 s[26:27], s13, v49
	v_cmp_le_u32_e64 s[28:29], s13, v50
	v_cmp_le_u32_e64 s[30:31], s13, v51
	v_cmp_le_u32_e64 s[34:35], s13, v52
	v_cmp_le_u32_e64 s[36:37], s13, v53
	v_cmp_le_u32_e64 s[38:39], s13, v54
	v_cmp_le_u32_e64 s[40:41], s13, v55
	s_bcnt1_i32_b64 s42, s[24:25]
	s_bcnt1_i32_b64 s43, s[26:27]
	s_bcnt1_i32_b64 s44, s[28:29]
	s_bcnt1_i32_b64 s45, s[30:31]
	s_bcnt1_i32_b64 s46, s[34:35]
	s_bcnt1_i32_b64 s47, s[36:37]
	s_bcnt1_i32_b64 s48, s[38:39]
	s_bcnt1_i32_b64 s49, s[40:41]
	s_add_i32 s14, s14, s42
	s_add_i32 s14, s14, s43
	s_add_i32 s14, s14, s44
	s_add_i32 s14, s14, s45
	v_add_u32_e32 v24, s46, v24
	v_add_u32_e32 v24, s47, v24
	v_add_u32_e32 v24, s48, v24
	v_add_u32_e32 v24, s49, v24
	s_cmp_lt_u32 s21, 4
	s_cbranch_scc1 .Ltk_dec
	v_cmp_le_u32_e64 s[24:25], s13, v56
	v_cmp_le_u32_e64 s[26:27], s13, v57
	v_cmp_le_u32_e64 s[28:29], s13, v58
	v_cmp_le_u32_e64 s[30:31], s13, v59
	v_cmp_le_u32_e64 s[34:35], s13, v60
	v_cmp_le_u32_e64 s[36:37], s13, v61
	v_cmp_le_u32_e64 s[38:39], s13, v62
	v_cmp_le_u32_e64 s[40:41], s13, v63
	s_bcnt1_i32_b64 s42, s[24:25]
	s_bcnt1_i32_b64 s43, s[26:27]
	s_bcnt1_i32_b64 s44, s[28:29]
	s_bcnt1_i32_b64 s45, s[30:31]
	s_bcnt1_i32_b64 s46, s[34:35]
	s_bcnt1_i32_b64 s47, s[36:37]
	s_bcnt1_i32_b64 s48, s[38:39]
	s_bcnt1_i32_b64 s49, s[40:41]
	s_add_i32 s14, s14, s42
	s_add_i32 s14, s14, s43
	s_add_i32 s14, s14, s44
	s_add_i32 s14, s14, s45
	v_add_u32_e32 v24, s46, v24
	v_add_u32_e32 v24, s47, v24
	v_add_u32_e32 v24, s48, v24
	v_add_u32_e32 v24, s49, v24

; #define TK_GRP(g) { const int c0 = __popcll(__ballot(u[4 * (g)] >= cand)), c1 = __popcll(__ballot(u[4 * (g) + 1] >= cand)), c2 = __popcll(__ballot(u[4 * (g) + 2] >= cand)), c3 = __popcll(__ballot(u[4 * (g) + 3] >= cand)); cnt += (c0 + c1) + (c2 + c3); }
; __device__ __forceinline__ void indexer_unit(const Args& a, LAS unsigned char* lds, LAS unsigned long long* maskl, int b, int qblk, int wave, int lane) {
;     ...
;                 const unsigned cand = T | (1u << bit); int cnt = 0;
;     ...
;                 switch (ng) {
;                     case 8: TK_GRP(7) [[fallthrough]];
;                     case 7: TK_GRP(6) [[fallthrough]];
;                     case 6: TK_GRP(5) [[fallthrough]];
;                     case 5: TK_GRP(4) [[fallthrough]];
;                     case 4: TK_GRP(3) [[fallthrough]];
;                     case 3: TK_GRP(2) [[fallthrough]];
;                     case 2: TK_GRP(1) [[fallthrough]];
;                     default: TK_GRP(0)
;                 }
;     ...
;                 if (cnt >= 256) { T = cand; if (cnt == 256) { exact = true; break; } }
;             }
;             int need = 0; const unsigned long long lt = (1ull << lane) - 1ull;
;             if (!exact) {
;                 int cl = 0;
; #pragma unroll
;                 for (int r = 0; r < 32; ++r) cl += (u[r] > T) ? 1 : 0;
;                 int ngt = 0;
; #pragma unroll
;                 for (int bb = 0; bb < 6; ++bb) ngt += __popcll(__ballot((cl >> bb) & 1)) << bb;
;                 need = 256 - ngt;
.Ltk_nxt:
	s_add_i32 s11, s11, -1
	s_cmp_ge_i32 s11, 0
	s_cbranch_scc1 .Ltk_bit
	v_mov_b32_e32 v100, 0
	v_mov_b32_e32 v101, 0
	v_mov_b32_e32 v24, 0
	v_cmp_lt_u32_e64 s[24:25], s10, v32
	v_cmp_lt_u32_e64 s[26:27], s10, v33
	v_cmp_lt_u32_e64 s[28:29], s10, v34
	v_cmp_lt_u32_e64 s[30:31], s10, v35
	v_cmp_lt_u32_e64 s[34:35], s10, v36
	v_cmp_lt_u32_e64 s[36:37], s10, v37
	v_cmp_lt_u32_e64 s[38:39], s10, v38
	v_cmp_lt_u32_e64 s[40:41], s10, v39
	s_bcnt1_i32_b64 s42, s[24:25]
	s_bcnt1_i32_b64 s43, s[26:27]
	s_bcnt1_i32_b64 s44, s[28:29]
	s_bcnt1_i32_b64 s45, s[30:31]
	s_bcnt1_i32_b64 s46, s[34:35]
	s_bcnt1_i32_b64 s47, s[36:37]
	s_bcnt1_i32_b64 s48, s[38:39]
	s_bcnt1_i32_b64 s49, s[40:41]
	s_add_i32 s14, s42, s43
	s_add_i32 s14, s14, s44
	s_add_i32 s14, s14, s45
	v_add_u32_e32 v24, s46, v24
	v_add_u32_e32 v24, s47, v24
	v_add_u32_e32 v24, s48, v24
	v_add_u32_e32 v24, s49, v24
	s_cmp_lt_u32 s21, 2
	s_cbranch_scc1 .Ltk_tie_cnt_done
	v_cmp_lt_u32_e64 s[24:25], s10, v40
	v_cmp_lt_u32_e64 s[26:27], s10, v41
	v_cmp_lt_u32_e64 s[28:29], s10, v42
	v_cmp_lt_u32_e64 s[30:31], s10, v43
	v_cmp_lt_u32_e64 s[34:35], s10, v44
	v_cmp_lt_u32_e64 s[36:37], s10, v45
	v_cmp_lt_u32_e64 s[38:39], s10, v46
	v_cmp_lt_u32_e64 s[40:41], s10, v47
	s_bcnt1_i32_b64 s42, s[24:25]
	s_bcnt1_i32_b64 s43, s[26:27]
	s_bcnt1_i32_b64 s44, s[28:29]
	s_bcnt1_i32_b64 s45, s[30:31]
	s_bcnt1_i32_b64 s46, s[34:35]
	s_bcnt1_i32_b64 s47, s[36:37]
	s_bcnt1_i32_b64 s48, s[38:39]
	s_bcnt1_i32_b64 s49, s[40:41]
	s_add_i32 s14, s14, s42
	s_add_i32 s14, s14, s43
	s_add_i32 s14, s14, s44
	s_add_i32 s14, s14, s45
	v_add_u32_e32 v24, s46, v24
	v_add_u32_e32 v24, s47, v24
	v_add_u32_e32 v24, s48, v24
	v_add_u32_e32 v24, s49, v24
	s_cmp_lt_u32 s21, 3
	s_cbranch_scc1 .Ltk_tie_cnt_done
	v_cmp_lt_u32_e64 s[24:25], s10, v48
	v_cmp_lt_u32_e64 s[26:27], s10, v49
	v_cmp_lt_u32_e64 s[28:29], s10, v50
	v_cmp_lt_u32_e64 s[30:31], s10, v51
	v_cmp_lt_u32_e64 s[34:35], s10, v52
	v_cmp_lt_u32_e64 s[36:37], s10, v53
	v_cmp_lt_u32_e64 s[38:39], s10, v54
	v_cmp_lt_u32_e64 s[40:41], s10, v55
	s_bcnt1_i32_b64 s42, s[24:25]
	s_bcnt1_i32_b64 s43, s[26:27]
	s_bcnt1_i32_b64 s44, s[28:29]
	s_bcnt1_i32_b64 s45, s[30:31]
	s_bcnt1_i32_b64 s46, s[34:35]
	s_bcnt1_i32_b64 s47, s[36:37]
	s_bcnt1_i32_b64 s48, s[38:39]
	s_bcnt1_i32_b64 s49, s[40:41]
	s_add_i32 s14, s14, s42
	s_add_i32 s14, s14, s43
	s_add_i32 s14, s14, s44
	s_add_i32 s14, s14, s45
	v_add_u32_e32 v24, s46, v24
	v_add_u32_e32 v24, s47, v24
	v_add_u32_e32 v24, s48, v24
	v_add_u32_e32 v24, s49, v24
	s_cmp_lt_u32 s21, 4
	s_cbranch_scc1 .Ltk_tie_cnt_done
	v_cmp_lt_u32_e64 s[24:25], s10, v56
	v_cmp_lt_u32_e64 s[26:27], s10, v57
	v_cmp_lt_u32_e64 s[28:29], s10, v58
	v_cmp_lt_u32_e64 s[30:31], s10, v59
	v_cmp_lt_u32_e64 s[34:35], s10, v60
	v_cmp_lt_u32_e64 s[36:37], s10, v61
	v_cmp_lt_u32_e64 s[38:39], s10, v62
	v_cmp_lt_u32_e64 s[40:41], s10, v63
	s_bcnt1_i32_b64 s42, s[24:25]
	s_bcnt1_i32_b64 s43, s[26:27]
	s_bcnt1_i32_b64 s44, s[28:29]
	s_bcnt1_i32_b64 s45, s[30:31]
	s_bcnt1_i32_b64 s46, s[34:35]
	s_bcnt1_i32_b64 s47, s[36:37]
	s_bcnt1_i32_b64 s48, s[38:39]
	s_bcnt1_i32_b64 s49, s[40:41]
	s_add_i32 s14, s14, s42
	s_add_i32 s14, s14, s43
	s_add_i32 s14, s14, s44
	s_add_i32 s14, s14, s45
	v_add_u32_e32 v24, s46, v24
	v_add_u32_e32 v24, s47, v24
	v_add_u32_e32 v24, s48, v24
	v_add_u32_e32 v24, s49, v24
